# P4 tile-to-block remap: blocks of one XCD share A row-tiles (A-stationary per XCD) to cut MALL->L2 traffic
# speedup vs baseline: 1.1414x; 1.0317x over previous
; DI unsigned pk2(float a, float b) { f2_t v = {a, b}; bf2_t r = __builtin_convertvector(v, bf2_t); return __builtin_bit_cast(unsigned, r); }
; DI void phase4(const Params& p, int l, char* lds) {
;     ...
;   for (int tile = blockIdx.x; tile < 128 * 8; tile += gridDim.x) {
;     const int nt = tile & 7, mt = tile >> 3;
;     f32x16 mg[2][2];
;     zero_acc(mg);
; #pragma unroll 1
;     for (int n = 0; n < 4; ++n) {
;       f32x16 acc[2][2];
;       zero_acc(acc);
;       gemm_mainloop_shallow(p.xn + (size_t)mt * 128 * 1024, 1024, WGT(l) + ((size_t)n * 1024 + nt * 128) * 1024, 1024, 1024, lds,
;     ...
; #pragma unroll
;     for (int mi = 0; mi < 2; ++mi) {
;       const size_t row = (size_t)mt * 128 + wm * 64 + mi * 32 + r;
; #pragma unroll
;       for (int ni = 0; ni < 2; ++ni)
; #pragma unroll
;         for (int a = 0; a < 4; ++a) {
;           const int col = nt * 128 + wn * 64 + ni * 32 + 8 * a + 4 * h;
;           uint2 o;
;           o.x = pk2(mg[mi][ni][4 * a], mg[mi][ni][4 * a + 1]);
;           o.y = pk2(mg[mi][ni][4 * a + 2], mg[mi][ni][4 * a + 3]);
;           *(uint2*)(p.z + row * ZS + col) = o;
;         }
;     }
.LBB0_1052:
	v_readlane_b32 s4, v255, 5
	s_lshl_b32 s0, s2, 7
	v_readlane_b32 s80, v253, 12
	v_readlane_b32 s86, v253, 18
	v_readlane_b32 s87, v253, 19
	v_readlane_b32 s88, v253, 20
	v_readlane_b32 s89, v253, 21
	v_readlane_b32 s81, v253, 13
	v_readlane_b32 s82, v253, 14
	v_readlane_b32 s83, v253, 15
	v_readlane_b32 s84, v253, 16
	v_readlane_b32 s85, v253, 17
	v_readlane_b32 s90, v253, 22
	v_readlane_b32 s91, v253, 23
	v_readlane_b32 s92, v253, 24
	v_readlane_b32 s93, v253, 25
	v_readlane_b32 s94, v253, 26
	v_readlane_b32 s95, v253, 27
	v_and_b32_e32 v170, 63, v209
	v_lshrrev_b32_e32 v171, 3, v170
	v_and_b32_e32 v172, 7, v170
	v_lshrrev_b32_e32 v173, 7, v209
	v_lshl_add_u32 v173, v173, 6, v171
	v_add_u32_e32 v174, s0, v173
	v_mul_lo_u32 v174, v174, s75
	v_and_b32_e32 v175, 64, v209
	v_add_u32_e32 v175, s4, v175
	v_lshlrev_b32_e32 v175, 1, v175
	v_lshl_add_u32 v175, v172, 4, v175
	v_add_u32_e32 v174, v174, v175
	v_lshrrev_b32_e32 v176, 6, v209
	v_mul_u32_u24_e32 v177, 0x2400, v176
	v_lshrrev_b32_e32 v176, 1, v176
	v_mul_u32_u24_e32 v176, 0x4800, v176
	v_add_u32_e32 v177, v177, v176
	v_add_u32_e32 v177, 0x4800, v177
	v_and_b32_e32 v178, 31, v170
	v_lshrrev_b32_e32 v179, 5, v170
	v_mul_u32_u24_e32 v178, 0x90, v178
	v_lshl_add_u32 v178, v179, 3, v178
	v_add_u32_e32 v178, v178, v177
	v_mul_u32_u24_e32 v179, 0x90, v171
	v_lshl_add_u32 v179, v172, 4, v179
	v_add_u32_e32 v179, v179, v177
	v_cvt_pk_f16_f32 v2, v144, v145
	v_cvt_pk_f16_f32 v3, v146, v147
	v_cvt_pk_f16_f32 v4, v140, v141
	v_cvt_pk_f16_f32 v5, v142, v143
	v_cvt_pk_f16_f32 v6, v136, v137
	v_cvt_pk_f16_f32 v7, v138, v139
	v_cvt_pk_f16_f32 v8, v134, v135
	v_cvt_pk_f16_f32 v9, v132, v133
	v_cvt_pk_f16_f32 v10, v128, v129
	v_cvt_pk_f16_f32 v11, v130, v131
	v_cvt_pk_f16_f32 v12, v124, v125
	v_cvt_pk_f16_f32 v13, v126, v127
	v_cvt_pk_f16_f32 v14, v120, v121
	v_cvt_pk_f16_f32 v15, v122, v123
	v_cvt_pk_f16_f32 v16, v118, v119
	v_cvt_pk_f16_f32 v17, v116, v117
	v_cvt_pk_f16_f32 v18, v112, v113
	v_cvt_pk_f16_f32 v19, v114, v115
	v_cvt_pk_f16_f32 v20, v108, v109
	v_cvt_pk_f16_f32 v21, v110, v111
	v_cvt_pk_f16_f32 v22, v104, v105
	v_cvt_pk_f16_f32 v23, v106, v107
	v_cvt_pk_f16_f32 v24, v102, v103
	v_cvt_pk_f16_f32 v25, v100, v101
	v_cvt_pk_f16_f32 v26, v96, v97
	v_cvt_pk_f16_f32 v27, v98, v99
	v_cvt_pk_f16_f32 v28, v92, v93
	v_cvt_pk_f16_f32 v29, v94, v95
	v_cvt_pk_f16_f32 v30, v88, v89
	v_cvt_pk_f16_f32 v31, v90, v91
	v_cvt_pk_f16_f32 v32, v86, v87
	v_cvt_pk_f16_f32 v33, v84, v85
	ds_write_b64 v178, v[2:3]
	ds_write_b64 v178, v[4:5] offset:16
	ds_write_b64 v178, v[6:7] offset:32
	ds_write_b64 v178, v[8:9] offset:48
	ds_write_b64 v178, v[10:11] offset:64
	ds_write_b64 v178, v[12:13] offset:80
	ds_write_b64 v178, v[14:15] offset:96
	ds_write_b64 v178, v[16:17] offset:112
	ds_write_b64 v178, v[18:19] offset:4608
	ds_write_b64 v178, v[20:21] offset:4624
	ds_write_b64 v178, v[22:23] offset:4640
	ds_write_b64 v178, v[24:25] offset:4656
	ds_write_b64 v178, v[26:27] offset:4672
	ds_write_b64 v178, v[28:29] offset:4688
	ds_write_b64 v178, v[30:31] offset:4704
	ds_write_b64 v178, v[32:33] offset:4720
	s_waitcnt lgkmcnt(0)
	ds_read_b128 v[34:37], v179
	ds_read_b128 v[38:41], v179 offset:1152
	ds_read_b128 v[42:45], v179 offset:2304
	ds_read_b128 v[46:49], v179 offset:3456
	ds_read_b128 v[50:53], v179 offset:4608
	ds_read_b128 v[54:57], v179 offset:5760
	ds_read_b128 v[58:61], v179 offset:6912
	ds_read_b128 v[62:65], v179 offset:8064
	s_add_i32 s17, s17, s30
	s_add_i32 s16, s16, s55
	s_waitcnt lgkmcnt(7)
	global_store_dwordx4 v174, v[34:37], s[86:87]
	v_add_u32_e32 v174, 0x19800, v174
	s_waitcnt lgkmcnt(6)
	global_store_dwordx4 v174, v[38:41], s[86:87]
	v_add_u32_e32 v174, 0x19800, v174
	s_waitcnt lgkmcnt(5)
	global_store_dwordx4 v174, v[42:45], s[86:87]
	v_add_u32_e32 v174, 0x19800, v174
	s_waitcnt lgkmcnt(4)
	global_store_dwordx4 v174, v[46:49], s[86:87]
	v_add_u32_e32 v174, 0x19800, v174
	s_waitcnt lgkmcnt(3)
	global_store_dwordx4 v174, v[50:53], s[86:87]
	v_add_u32_e32 v174, 0x19800, v174
	s_waitcnt lgkmcnt(2)
	global_store_dwordx4 v174, v[54:57], s[86:87]
	v_add_u32_e32 v174, 0x19800, v174
	s_waitcnt lgkmcnt(1)
	global_store_dwordx4 v174, v[58:61], s[86:87]
	v_add_u32_e32 v174, 0x19800, v174
	s_waitcnt lgkmcnt(0)
	global_store_dwordx4 v174, v[62:65], s[86:87]
	s_cmpk_gt_i32 s17, 0x3ff
	s_cbranch_scc1 .LBB0_1060
.LBB0_1053:
	s_and_b32 s0, s17, 7
	s_lshr_b32 s1, s17, 3
	s_and_b32 s1, s1, 63
	s_lshr_b32 s2, s17, 9
	s_lshl_b32 s2, s2, 3
	s_lshr_b32 s18, s1, 3
	s_add_i32 s2, s2, s18
	s_lshl_b32 s2, s2, 3
	s_add_i32 s2, s2, s0
	s_and_b32 s1, s1, 7
	s_lshl_b32 s18, s1, 7
	s_lshl_b32 s0, s1, 17
	v_writelane_b32 v255, s18, 5
	s_lshl_b32 s18, s1, 18
	s_add_u32 s0, s12, s0
	s_addc_u32 s1, s13, 0
	s_add_u32 s18, s14, s18
	s_addc_u32 s19, s15, 0
	s_ashr_i32 s3, s2, 31
	s_lshl_b64 s[4:5], s[2:3], 18
	s_add_u32 s4, s88, s4
	s_mul_i32 s7, s2, 0x198000
	s_addc_u32 s5, s89, s5
	s_mul_hi_i32 s6, s2, 0x198000
	s_add_u32 s20, s86, s7
	v_mov_b32_e32 v84, 0
	s_addc_u32 s21, s87, s6
	s_mov_b32 s22, 0
	s_mov_b64 s[6:7], 0
	v_mov_b32_e32 v85, v84
	v_mov_b32_e32 v96, v84
	v_mov_b32_e32 v97, v84
	v_mov_b32_e32 v98, v84
	v_mov_b32_e32 v99, v84
	v_mov_b32_e32 v92, v84
	v_mov_b32_e32 v93, v84
	v_mov_b32_e32 v94, v84
	v_mov_b32_e32 v95, v84
	v_mov_b32_e32 v88, v84
	v_mov_b32_e32 v89, v84
	v_mov_b32_e32 v90, v84
	v_mov_b32_e32 v91, v84
	v_mov_b32_e32 v86, v84
	v_mov_b32_e32 v87, v84
	v_mov_b32_e32 v100, v84
	v_mov_b32_e32 v101, v84
	v_mov_b32_e32 v112, v84
	v_mov_b32_e32 v113, v84
	v_mov_b32_e32 v114, v84
	v_mov_b32_e32 v115, v84
	v_mov_b32_e32 v108, v84
	v_mov_b32_e32 v109, v84
	v_mov_b32_e32 v110, v84
	v_mov_b32_e32 v111, v84
	v_mov_b32_e32 v104, v84
	v_mov_b32_e32 v105, v84
	v_mov_b32_e32 v106, v84
	v_mov_b32_e32 v107, v84
	v_mov_b32_e32 v102, v84
	v_mov_b32_e32 v103, v84
	v_mov_b32_e32 v116, v84
	v_mov_b32_e32 v117, v84
	v_mov_b32_e32 v128, v84
	v_mov_b32_e32 v129, v84
	v_mov_b32_e32 v130, v84
	v_mov_b32_e32 v131, v84
	v_mov_b32_e32 v124, v84
	v_mov_b32_e32 v125, v84
	v_mov_b32_e32 v126, v84
	v_mov_b32_e32 v127, v84
	v_mov_b32_e32 v120, v84
	v_mov_b32_e32 v121, v84
	v_mov_b32_e32 v122, v84
	v_mov_b32_e32 v123, v84
	v_mov_b32_e32 v118, v84
	v_mov_b32_e32 v119, v84
	v_mov_b32_e32 v132, v84
	v_mov_b32_e32 v133, v84
	v_mov_b32_e32 v144, v84
	v_mov_b32_e32 v145, v84
	v_mov_b32_e32 v146, v84
	v_mov_b32_e32 v147, v84
	v_mov_b32_e32 v140, v84
	v_mov_b32_e32 v141, v84
	v_mov_b32_e32 v142, v84
	v_mov_b32_e32 v143, v84
	v_mov_b32_e32 v136, v84
	v_mov_b32_e32 v137, v84
	v_mov_b32_e32 v138, v84
	v_mov_b32_e32 v139, v84
	v_mov_b32_e32 v134, v84
	v_mov_b32_e32 v135, v84
	s_branch .LBB0_1055
